# qb epilogue: lean fast path for non-rotary tiles (hoisted SSQ loads, counted vmcnt); swiglu rs^2 folded into reciprocal; scalar has_next compare
# baseline (speedup 1.0000x reference)
;     __host__ __device__ bool next(int i, Unit& u) const {
;         const long L = (long)i * G + c; if (L >= nwg) return false;
;         int wgid = (int)L; { const int q = nwg / NXCD, r = nwg % NXCD, xcd = wgid % NXCD, off = wgid / NXCD; wgid = (xcd < r ? xcd * (q + 1) : r * (q + 1) + (xcd - r) * q) + off; }
;         const int nig = WGM * nN, gid = wgid / nig, fm = gid * WGM, gsz = (nM - fm) < WGM ? (nM - fm) : WGM;
;         u.pm = fm + ((wgid % nig) % gsz); u.pn = (wgid % nig) / gsz; return true;
.LBB0_499:
	s_add_i32 s43, s30, 1
	v_readlane_b32 s10, v254, 55
	s_mul_i32 s10, s43, s10
	s_mul_hi_u32 s11, s43, s90
	s_add_i32 s11, s11, s10
	s_mul_i32 s10, s43, s90
	s_add_u32 s10, s10, s91
	v_readlane_b32 s12, v254, 56
	s_addc_u32 s11, s11, s12
	v_readlane_b32 s12, v254, 32
	s_cmp_lt_u32 s10, s12
	s_cselect_b64 s[12:13], -1, 0
	s_cbranch_scc0 .LBB0_501
	s_ashr_i32 s11, s10, 31
	s_lshr_b32 s11, s11, 29
	s_add_i32 s11, s10, s11
	s_ashr_i32 s16, s11, 3
	s_and_b32 s11, s11, -8
	s_sub_i32 s10, s10, s11
	s_lshr_b32 s11, s10, 31
	v_readlane_b32 s20, v254, 36
	s_or_b32 s11, s20, s11
	s_mul_i32 s10, s11, s10
	s_add_i32 s10, s10, s16
	s_ashr_i32 s11, s10, 31
	v_readlane_b32 s16, v254, 37
	s_xor_b32 s11, s11, s16
	s_abs_i32 s16, s10
	v_readlane_b32 s17, v254, 38
	s_mul_hi_u32 s17, s16, s17
	s_mul_i32 s18, s17, s49
	s_sub_i32 s16, s16, s18
	s_add_i32 s18, s17, 1
	s_sub_i32 s19, s16, s49
	s_cmp_ge_u32 s16, s49
	s_cselect_b32 s17, s18, s17
	s_cselect_b32 s16, s19, s16
	s_add_i32 s18, s17, 1
	s_cmp_ge_u32 s16, s49
	s_cselect_b32 s16, s18, s17
	s_xor_b32 s16, s16, s11
	s_sub_i32 s11, s16, s11
	s_lshl_b32 s16, s11, 3
	s_mul_i32 s11, s11, s20
	s_sub_i32 s10, s10, s11
	s_lshr_b32 s38, s10, 3
	s_and_b32 s10, s10, 7
	s_add_i32 s80, s10, s16

; __device__ __forceinline__ u32x4 pack8(const f32x4& a, const f32x4& b, float sc) { u32x4 w; w[0] = pk2(a[0] * sc, a[1] * sc); w[1] = pk2(a[2] * sc, a[3] * sc); w[2] = pk2(b[0] * sc, b[1] * sc); w[3] = pk2(b[2] * sc, b[3] * sc); return w; }
; __device__ __forceinline__ void epi_qb(const MixBufs B, const f32x2* ROPE, const f32x4 (&acc)[2][2][4][2], const Unit& u, int wr, int wc, int fr, int fq) {
;     const int pn = u.pn;
;     const bool roped = pn >= 4;
;     bf16_t* dst = roped ? mQM(B) + ((pn - 4) * 4 + wc) * 192 + 128 : mQM(B) + (2 * pn) * 192 + wc * 32;
;     const int loff = fq * 8;
;     Rope8 R[2]; f32x4 sq[2][2];
;     { const int r0 = opaque(EPI_ROW(0)); if (roped) rope_load(R[0], ROPE, r0, fq * 8); const f32x4* p = (const f32x4*)(mSSQ(B) + (size_t)r0 * 8); sq[0][0] = p[0]; sq[0][1] = p[1]; }
; #pragma unroll
;     for (int it = 0; it < 8; ++it) {
;         const int ai = it >> 2, m = it & 3; const int r = opaque(EPI_ROW(it));
;         if (it + 1 < 8) { const int rn = opaque(EPI_ROW(it + 1)); if (roped) rope_load(R[(it + 1) & 1], ROPE, rn, fq * 8);
;             const f32x4* p = (const f32x4*)(mSSQ(B) + (size_t)rn * 8); sq[(it + 1) & 1][0] = p[0]; sq[(it + 1) & 1][1] = p[1]; }
;         const f32x4 sv = sq[it & 1][0] + sq[it & 1][1];
;         const float rs = rsqrtf(((sv[0] + sv[1]) + (sv[2] + sv[3])) * (1.0f / 512) + RMS_EPS) * QSCALE_M;
;         const f32x4 (&a0)[2] = acc[ai][0][m]; const f32x4 (&a1)[2] = acc[ai][1][m];
;         bf16_t* p = dst + (size_t)r * 1536 + loff;
;         if (!roped) { *(u32x4*)p = pack8(a0[0], a0[1], rs); *(u32x4*)(p + 192) = pack8(a1[0], a1[1], rs); }
;         else { u32x4 w1, w2; rope8(a0, a1, rs, R[it & 1], w1, w2); *(u32x4*)p = w1; *(u32x4*)(p + 32) = w2; }
;         asm volatile("" ::: "memory");
;     }
; }
.LBB0_524:
	s_andn2_b64 vcc, exec, s[2:3]
	s_cbranch_vccnz .LBB0_578
	s_cmp_gt_i32 s77, 3
	s_cbranch_scc1 .Lqb_orig
	s_mov_b64 s[2:3], s[96:97]
	s_mul_i32 s14, s77, 0x300
	v_readlane_b32 s16, v255, 1
	s_lshl_b32 s16, s16, 1
	s_add_i32 s14, s14, s16
	s_add_u32 s12, s2, 0x1e1c1000
	s_addc_u32 s13, s3, 0
	s_add_u32 s12, s12, s14
	s_addc_u32 s13, s13, 0
	s_add_u32 s14, s2, 0x19600000
	s_addc_u32 s15, s3, 0
	s_lshl_b32 s16, s81, 8
	s_waitcnt lgkmcnt(0)
	v_add_u32_e32 v130, s16, v193
	v_lshlrev_b32_e32 v246, 5, v130
	v_add_u32_e32 v247, 0x1000, v246
	v_mul_u32_u24_e32 v130, 0xc00, v130
	v_lshl_add_u32 v130, v192, 1, v130
	global_load_dwordx4 v[132:135], v246, s[14:15]
	global_load_dwordx4 v[136:139], v246, s[14:15] offset:16
	global_load_dwordx4 v[140:143], v246, s[14:15] offset:512
	global_load_dwordx4 v[144:147], v246, s[14:15] offset:528
	global_load_dwordx4 v[148:151], v246, s[14:15] offset:1024
	global_load_dwordx4 v[152:155], v246, s[14:15] offset:1040
	global_load_dwordx4 v[156:159], v246, s[14:15] offset:1536
	global_load_dwordx4 v[160:163], v246, s[14:15] offset:1552
	global_load_dwordx4 v[164:167], v247, s[14:15]
	global_load_dwordx4 v[168:171], v247, s[14:15] offset:16
	global_load_dwordx4 v[172:175], v247, s[14:15] offset:512
	global_load_dwordx4 v[176:179], v247, s[14:15] offset:528
	global_load_dwordx4 v[200:203], v247, s[14:15] offset:1024
	global_load_dwordx4 v[204:207], v247, s[14:15] offset:1040
	global_load_dwordx4 v[208:211], v247, s[14:15] offset:1536
	global_load_dwordx4 v[212:215], v247, s[14:15] offset:1552
	s_waitcnt vmcnt(14)
	v_pk_add_f32 v[132:133], v[132:133], v[136:137]
	v_pk_add_f32 v[134:135], v[134:135], v[138:139]
	v_add_f32_e32 v180, v132, v133
	v_add_f32_e32 v181, v134, v135
	v_add_f32_e32 v180, v180, v181
	v_fmamk_f32 v180, v180, 0x3b000000, v222
	v_mul_f32_e32 v181, 0x4b800000, v180
	v_cmp_gt_f32_e32 vcc, s92, v180
	s_nop 1
	v_cndmask_b32_e32 v180, v180, v181, vcc
	v_rsq_f32_e32 v180, v180
	s_nop 0
	v_mul_f32_e32 v181, 0x45800000, v180
	v_cndmask_b32_e32 v180, v180, v181, vcc
	v_mul_f32_e32 v244, 0x3dd53b94, v180
	v_pk_mul_f32 v[126:127], v[126:127], v[244:245] op_sel_hi:[1,0]
	v_pk_mul_f32 v[128:129], v[128:129], v[244:245] op_sel_hi:[1,0]
	v_pk_mul_f32 v[118:119], v[118:119], v[244:245] op_sel_hi:[1,0]
	v_pk_mul_f32 v[120:121], v[120:121], v[244:245] op_sel_hi:[1,0]
	v_cvt_pk_bf16_f32 v132, v126, v127
	v_cvt_pk_bf16_f32 v133, v128, v129
	v_cvt_pk_bf16_f32 v134, v118, v119
	v_cvt_pk_bf16_f32 v135, v120, v121
	global_store_dwordx4 v130, v[132:135], s[12:13]
	v_pk_mul_f32 v[122:123], v[122:123], v[244:245] op_sel_hi:[1,0]
	v_pk_mul_f32 v[124:125], v[124:125], v[244:245] op_sel_hi:[1,0]
	v_pk_mul_f32 v[114:115], v[114:115], v[244:245] op_sel_hi:[1,0]
	v_pk_mul_f32 v[116:117], v[116:117], v[244:245] op_sel_hi:[1,0]
	v_cvt_pk_bf16_f32 v136, v122, v123
	v_cvt_pk_bf16_f32 v137, v124, v125
	v_cvt_pk_bf16_f32 v138, v114, v115
	v_cvt_pk_bf16_f32 v139, v116, v117
	global_store_dwordx4 v130, v[136:139], s[12:13] offset:384
	s_waitcnt vmcnt(14)
	v_pk_add_f32 v[140:141], v[140:141], v[144:145]
	v_pk_add_f32 v[142:143], v[142:143], v[146:147]
	v_add_f32_e32 v180, v140, v141
	v_add_f32_e32 v181, v142, v143
	v_add_f32_e32 v180, v180, v181
	v_fmamk_f32 v180, v180, 0x3b000000, v222
	v_mul_f32_e32 v181, 0x4b800000, v180
	v_cmp_gt_f32_e32 vcc, s92, v180
	s_nop 1
	v_cndmask_b32_e32 v180, v180, v181, vcc
	v_rsq_f32_e32 v180, v180
	s_nop 0
	v_mul_f32_e32 v181, 0x45800000, v180
	v_cndmask_b32_e32 v180, v180, v181, vcc
	v_mul_f32_e32 v244, 0x3dd53b94, v180
	v_add_u32_e32 v131, 0xc000, v130
	v_pk_mul_f32 v[110:111], v[110:111], v[244:245] op_sel_hi:[1,0]
	v_pk_mul_f32 v[112:113], v[112:113], v[244:245] op_sel_hi:[1,0]
	v_pk_mul_f32 v[102:103], v[102:103], v[244:245] op_sel_hi:[1,0]
	v_pk_mul_f32 v[104:105], v[104:105], v[244:245] op_sel_hi:[1,0]
	v_cvt_pk_bf16_f32 v140, v110, v111
	v_cvt_pk_bf16_f32 v141, v112, v113
	v_cvt_pk_bf16_f32 v142, v102, v103
	v_cvt_pk_bf16_f32 v143, v104, v105
	global_store_dwordx4 v131, v[140:143], s[12:13]
	v_pk_mul_f32 v[106:107], v[106:107], v[244:245] op_sel_hi:[1,0]
	v_pk_mul_f32 v[108:109], v[108:109], v[244:245] op_sel_hi:[1,0]
	v_pk_mul_f32 v[98:99], v[98:99], v[244:245] op_sel_hi:[1,0]
	v_pk_mul_f32 v[100:101], v[100:101], v[244:245] op_sel_hi:[1,0]
	v_cvt_pk_bf16_f32 v144, v106, v107
	v_cvt_pk_bf16_f32 v145, v108, v109
	v_cvt_pk_bf16_f32 v146, v98, v99
	v_cvt_pk_bf16_f32 v147, v100, v101
	global_store_dwordx4 v131, v[144:147], s[12:13] offset:384
	s_waitcnt vmcnt(14)
	v_pk_add_f32 v[148:149], v[148:149], v[152:153]
	v_pk_add_f32 v[150:151], v[150:151], v[154:155]
	v_add_f32_e32 v180, v148, v149
	v_add_f32_e32 v181, v150, v151
	v_add_f32_e32 v180, v180, v181
	v_fmamk_f32 v180, v180, 0x3b000000, v222
	v_mul_f32_e32 v181, 0x4b800000, v180
	v_cmp_gt_f32_e32 vcc, s92, v180
	s_nop 1
	v_cndmask_b32_e32 v180, v180, v181, vcc
	v_rsq_f32_e32 v180, v180
	s_nop 0
	v_mul_f32_e32 v181, 0x45800000, v180
	v_cndmask_b32_e32 v180, v180, v181, vcc
	v_mul_f32_e32 v244, 0x3dd53b94, v180
	v_add_u32_e32 v131, 0x18000, v130
	v_pk_mul_f32 v[94:95], v[94:95], v[244:245] op_sel_hi:[1,0]
	v_pk_mul_f32 v[96:97], v[96:97], v[244:245] op_sel_hi:[1,0]
	v_pk_mul_f32 v[86:87], v[86:87], v[244:245] op_sel_hi:[1,0]
	v_pk_mul_f32 v[88:89], v[88:89], v[244:245] op_sel_hi:[1,0]
	v_cvt_pk_bf16_f32 v148, v94, v95
	v_cvt_pk_bf16_f32 v149, v96, v97
	v_cvt_pk_bf16_f32 v150, v86, v87
	v_cvt_pk_bf16_f32 v151, v88, v89
	global_store_dwordx4 v131, v[148:151], s[12:13]
	v_pk_mul_f32 v[90:91], v[90:91], v[244:245] op_sel_hi:[1,0]
	v_pk_mul_f32 v[92:93], v[92:93], v[244:245] op_sel_hi:[1,0]
	v_pk_mul_f32 v[82:83], v[82:83], v[244:245] op_sel_hi:[1,0]
	v_pk_mul_f32 v[84:85], v[84:85], v[244:245] op_sel_hi:[1,0]
	v_cvt_pk_bf16_f32 v152, v90, v91
	v_cvt_pk_bf16_f32 v153, v92, v93
	v_cvt_pk_bf16_f32 v154, v82, v83
	v_cvt_pk_bf16_f32 v155, v84, v85
	global_store_dwordx4 v131, v[152:155], s[12:13] offset:384
	s_waitcnt vmcnt(14)
; __device__ __forceinline__ u32x4 pack8(const f32x4& a, const f32x4& b, float sc) { u32x4 w; w[0] = pk2(a[0] * sc, a[1] * sc); w[1] = pk2(a[2] * sc, a[3] * sc); w[2] = pk2(b[0] * sc, b[1] * sc); w[3] = pk2(b[2] * sc, b[3] * sc); return w; }
; __device__ __forceinline__ void epi_qb(const MixBufs B, const f32x2* ROPE, const f32x4 (&acc)[2][2][4][2], const Unit& u, int wr, int wc, int fr, int fq) {
;     ...
;     for (int it = 0; it < 8; ++it) {
;         const int ai = it >> 2, m = it & 3; const int r = opaque(EPI_ROW(it));
;         if (it + 1 < 8) { const int rn = opaque(EPI_ROW(it + 1)); if (roped) rope_load(R[(it + 1) & 1], ROPE, rn, fq * 8);
;             const f32x4* p = (const f32x4*)(mSSQ(B) + (size_t)rn * 8); sq[(it + 1) & 1][0] = p[0]; sq[(it + 1) & 1][1] = p[1]; }
;         const f32x4 sv = sq[it & 1][0] + sq[it & 1][1];
;         const float rs = rsqrtf(((sv[0] + sv[1]) + (sv[2] + sv[3])) * (1.0f / 512) + RMS_EPS) * QSCALE_M;
;         const f32x4 (&a0)[2] = acc[ai][0][m]; const f32x4 (&a1)[2] = acc[ai][1][m];
;         bf16_t* p = dst + (size_t)r * 1536 + loff;
;         if (!roped) { *(u32x4*)p = pack8(a0[0], a0[1], rs); *(u32x4*)(p + 192) = pack8(a1[0], a1[1], rs); }
;         else { u32x4 w1, w2; rope8(a0, a1, rs, R[it & 1], w1, w2); *(u32x4*)p = w1; *(u32x4*)(p + 32) = w2; }
;         asm volatile("" ::: "memory");
	v_pk_add_f32 v[156:157], v[156:157], v[160:161]
	v_pk_add_f32 v[158:159], v[158:159], v[162:163]
	v_add_f32_e32 v180, v156, v157
	v_add_f32_e32 v181, v158, v159
	v_add_f32_e32 v180, v180, v181
	v_fmamk_f32 v180, v180, 0x3b000000, v222
	v_mul_f32_e32 v181, 0x4b800000, v180
	v_cmp_gt_f32_e32 vcc, s92, v180
	s_nop 1
	v_cndmask_b32_e32 v180, v180, v181, vcc
	v_rsq_f32_e32 v180, v180
	s_nop 0
	v_mul_f32_e32 v181, 0x45800000, v180
	v_cndmask_b32_e32 v180, v180, v181, vcc
	v_mul_f32_e32 v244, 0x3dd53b94, v180
	v_add_u32_e32 v131, 0x24000, v130
	v_pk_mul_f32 v[78:79], v[78:79], v[244:245] op_sel_hi:[1,0]
	v_pk_mul_f32 v[80:81], v[80:81], v[244:245] op_sel_hi:[1,0]
	v_pk_mul_f32 v[70:71], v[70:71], v[244:245] op_sel_hi:[1,0]
	v_pk_mul_f32 v[72:73], v[72:73], v[244:245] op_sel_hi:[1,0]
	v_cvt_pk_bf16_f32 v156, v78, v79
	v_cvt_pk_bf16_f32 v157, v80, v81
	v_cvt_pk_bf16_f32 v158, v70, v71
	v_cvt_pk_bf16_f32 v159, v72, v73
	global_store_dwordx4 v131, v[156:159], s[12:13]
	v_pk_mul_f32 v[74:75], v[74:75], v[244:245] op_sel_hi:[1,0]
	v_pk_mul_f32 v[76:77], v[76:77], v[244:245] op_sel_hi:[1,0]
	v_pk_mul_f32 v[66:67], v[66:67], v[244:245] op_sel_hi:[1,0]
	v_pk_mul_f32 v[68:69], v[68:69], v[244:245] op_sel_hi:[1,0]
	v_cvt_pk_bf16_f32 v160, v74, v75
	v_cvt_pk_bf16_f32 v161, v76, v77
	v_cvt_pk_bf16_f32 v162, v66, v67
	v_cvt_pk_bf16_f32 v163, v68, v69
	global_store_dwordx4 v131, v[160:163], s[12:13] offset:384
	s_waitcnt vmcnt(14)
	v_pk_add_f32 v[164:165], v[164:165], v[168:169]
	v_pk_add_f32 v[166:167], v[166:167], v[170:171]
	v_add_f32_e32 v180, v164, v165
	v_add_f32_e32 v181, v166, v167
	v_add_f32_e32 v180, v180, v181
	v_fmamk_f32 v180, v180, 0x3b000000, v222
	v_mul_f32_e32 v181, 0x4b800000, v180
	v_cmp_gt_f32_e32 vcc, s92, v180
	s_nop 1
	v_cndmask_b32_e32 v180, v180, v181, vcc
	v_rsq_f32_e32 v180, v180
	s_nop 0
	v_mul_f32_e32 v181, 0x45800000, v180
	v_cndmask_b32_e32 v180, v180, v181, vcc
	v_mul_f32_e32 v244, 0x3dd53b94, v180
	v_add_u32_e32 v131, 0x60000, v130
	v_pk_mul_f32 v[62:63], v[62:63], v[244:245] op_sel_hi:[1,0]
	v_pk_mul_f32 v[64:65], v[64:65], v[244:245] op_sel_hi:[1,0]
	v_pk_mul_f32 v[54:55], v[54:55], v[244:245] op_sel_hi:[1,0]
	v_pk_mul_f32 v[56:57], v[56:57], v[244:245] op_sel_hi:[1,0]
	v_cvt_pk_bf16_f32 v164, v62, v63
	v_cvt_pk_bf16_f32 v165, v64, v65
	v_cvt_pk_bf16_f32 v166, v54, v55
	v_cvt_pk_bf16_f32 v167, v56, v57
	global_store_dwordx4 v131, v[164:167], s[12:13]
	v_pk_mul_f32 v[58:59], v[58:59], v[244:245] op_sel_hi:[1,0]
	v_pk_mul_f32 v[60:61], v[60:61], v[244:245] op_sel_hi:[1,0]
	v_pk_mul_f32 v[50:51], v[50:51], v[244:245] op_sel_hi:[1,0]
	v_pk_mul_f32 v[52:53], v[52:53], v[244:245] op_sel_hi:[1,0]
	v_cvt_pk_bf16_f32 v168, v58, v59
	v_cvt_pk_bf16_f32 v169, v60, v61
	v_cvt_pk_bf16_f32 v170, v50, v51
	v_cvt_pk_bf16_f32 v171, v52, v53
	global_store_dwordx4 v131, v[168:171], s[12:13] offset:384
	s_waitcnt vmcnt(14)
	v_pk_add_f32 v[172:173], v[172:173], v[176:177]
	v_pk_add_f32 v[174:175], v[174:175], v[178:179]
	v_add_f32_e32 v180, v172, v173
	v_add_f32_e32 v181, v174, v175
	v_add_f32_e32 v180, v180, v181
	v_fmamk_f32 v180, v180, 0x3b000000, v222
	v_mul_f32_e32 v181, 0x4b800000, v180
	v_cmp_gt_f32_e32 vcc, s92, v180
	s_nop 1
	v_cndmask_b32_e32 v180, v180, v181, vcc
	v_rsq_f32_e32 v180, v180
	s_nop 0
	v_mul_f32_e32 v181, 0x45800000, v180
	v_cndmask_b32_e32 v180, v180, v181, vcc
	v_mul_f32_e32 v244, 0x3dd53b94, v180
	v_add_u32_e32 v131, 0x6c000, v130
	v_pk_mul_f32 v[46:47], v[46:47], v[244:245] op_sel_hi:[1,0]
	v_pk_mul_f32 v[48:49], v[48:49], v[244:245] op_sel_hi:[1,0]
	v_pk_mul_f32 v[38:39], v[38:39], v[244:245] op_sel_hi:[1,0]
	v_pk_mul_f32 v[40:41], v[40:41], v[244:245] op_sel_hi:[1,0]
	v_cvt_pk_bf16_f32 v172, v46, v47
	v_cvt_pk_bf16_f32 v173, v48, v49
	v_cvt_pk_bf16_f32 v174, v38, v39
	v_cvt_pk_bf16_f32 v175, v40, v41
	global_store_dwordx4 v131, v[172:175], s[12:13]
	v_pk_mul_f32 v[42:43], v[42:43], v[244:245] op_sel_hi:[1,0]
	v_pk_mul_f32 v[44:45], v[44:45], v[244:245] op_sel_hi:[1,0]
	v_pk_mul_f32 v[34:35], v[34:35], v[244:245] op_sel_hi:[1,0]
	v_pk_mul_f32 v[36:37], v[36:37], v[244:245] op_sel_hi:[1,0]
	v_cvt_pk_bf16_f32 v176, v42, v43
	v_cvt_pk_bf16_f32 v177, v44, v45
	v_cvt_pk_bf16_f32 v178, v34, v35
	v_cvt_pk_bf16_f32 v179, v36, v37
	global_store_dwordx4 v131, v[176:179], s[12:13] offset:384
	s_waitcnt vmcnt(14)
; __device__ __forceinline__ u32x4 pack8(const f32x4& a, const f32x4& b, float sc) { u32x4 w; w[0] = pk2(a[0] * sc, a[1] * sc); w[1] = pk2(a[2] * sc, a[3] * sc); w[2] = pk2(b[0] * sc, b[1] * sc); w[3] = pk2(b[2] * sc, b[3] * sc); return w; }
; __device__ __forceinline__ void epi_qb(const MixBufs B, const f32x2* ROPE, const f32x4 (&acc)[2][2][4][2], const Unit& u, int wr, int wc, int fr, int fq) {
;     const int pn = u.pn;
;     const bool roped = pn >= 4;
;     bf16_t* dst = roped ? mQM(B) + ((pn - 4) * 4 + wc) * 192 + 128 : mQM(B) + (2 * pn) * 192 + wc * 32;
;     const int loff = fq * 8;
;     Rope8 R[2]; f32x4 sq[2][2];
;     { const int r0 = opaque(EPI_ROW(0)); if (roped) rope_load(R[0], ROPE, r0, fq * 8); const f32x4* p = (const f32x4*)(mSSQ(B) + (size_t)r0 * 8); sq[0][0] = p[0]; sq[0][1] = p[1]; }
;     ...
;     for (int it = 0; it < 8; ++it) {
;         const int ai = it >> 2, m = it & 3; const int r = opaque(EPI_ROW(it));
;         if (it + 1 < 8) { const int rn = opaque(EPI_ROW(it + 1)); if (roped) rope_load(R[(it + 1) & 1], ROPE, rn, fq * 8);
;             const f32x4* p = (const f32x4*)(mSSQ(B) + (size_t)rn * 8); sq[(it + 1) & 1][0] = p[0]; sq[(it + 1) & 1][1] = p[1]; }
;         const f32x4 sv = sq[it & 1][0] + sq[it & 1][1];
;         const float rs = rsqrtf(((sv[0] + sv[1]) + (sv[2] + sv[3])) * (1.0f / 512) + RMS_EPS) * QSCALE_M;
;         const f32x4 (&a0)[2] = acc[ai][0][m]; const f32x4 (&a1)[2] = acc[ai][1][m];
;         bf16_t* p = dst + (size_t)r * 1536 + loff;
;         if (!roped) { *(u32x4*)p = pack8(a0[0], a0[1], rs); *(u32x4*)(p + 192) = pack8(a1[0], a1[1], rs); }
;         else { u32x4 w1, w2; rope8(a0, a1, rs, R[it & 1], w1, w2); *(u32x4*)p = w1; *(u32x4*)(p + 32) = w2; }
;         asm volatile("" ::: "memory");
	v_pk_add_f32 v[200:201], v[200:201], v[204:205]
	v_pk_add_f32 v[202:203], v[202:203], v[206:207]
	v_add_f32_e32 v180, v200, v201
	v_add_f32_e32 v181, v202, v203
	v_add_f32_e32 v180, v180, v181
	v_fmamk_f32 v180, v180, 0x3b000000, v222
	v_mul_f32_e32 v181, 0x4b800000, v180
	v_cmp_gt_f32_e32 vcc, s92, v180
	s_nop 1
	v_cndmask_b32_e32 v180, v180, v181, vcc
	v_rsq_f32_e32 v180, v180
	s_nop 0
	v_mul_f32_e32 v181, 0x45800000, v180
	v_cndmask_b32_e32 v180, v180, v181, vcc
	v_mul_f32_e32 v244, 0x3dd53b94, v180
	v_add_u32_e32 v131, 0x78000, v130
	v_pk_mul_f32 v[30:31], v[30:31], v[244:245] op_sel_hi:[1,0]
	v_pk_mul_f32 v[32:33], v[32:33], v[244:245] op_sel_hi:[1,0]
	v_pk_mul_f32 v[22:23], v[22:23], v[244:245] op_sel_hi:[1,0]
	v_pk_mul_f32 v[24:25], v[24:25], v[244:245] op_sel_hi:[1,0]
	v_cvt_pk_bf16_f32 v200, v30, v31
	v_cvt_pk_bf16_f32 v201, v32, v33
	v_cvt_pk_bf16_f32 v202, v22, v23
	v_cvt_pk_bf16_f32 v203, v24, v25
	global_store_dwordx4 v131, v[200:203], s[12:13]
	v_pk_mul_f32 v[26:27], v[26:27], v[244:245] op_sel_hi:[1,0]
	v_pk_mul_f32 v[28:29], v[28:29], v[244:245] op_sel_hi:[1,0]
	v_pk_mul_f32 v[18:19], v[18:19], v[244:245] op_sel_hi:[1,0]
	v_pk_mul_f32 v[20:21], v[20:21], v[244:245] op_sel_hi:[1,0]
	v_cvt_pk_bf16_f32 v204, v26, v27
	v_cvt_pk_bf16_f32 v205, v28, v29
	v_cvt_pk_bf16_f32 v206, v18, v19
	v_cvt_pk_bf16_f32 v207, v20, v21
	global_store_dwordx4 v131, v[204:207], s[12:13] offset:384
	s_waitcnt vmcnt(14)
	v_pk_add_f32 v[208:209], v[208:209], v[212:213]
	v_pk_add_f32 v[210:211], v[210:211], v[214:215]
	v_add_f32_e32 v180, v208, v209
	v_add_f32_e32 v181, v210, v211
	v_add_f32_e32 v180, v180, v181
	v_fmamk_f32 v180, v180, 0x3b000000, v222
	v_mul_f32_e32 v181, 0x4b800000, v180
	v_cmp_gt_f32_e32 vcc, s92, v180
	s_nop 1
	v_cndmask_b32_e32 v180, v180, v181, vcc
	v_rsq_f32_e32 v180, v180
	s_nop 0
	v_mul_f32_e32 v181, 0x45800000, v180
	v_cndmask_b32_e32 v180, v180, v181, vcc
	v_mul_f32_e32 v244, 0x3dd53b94, v180
	v_add_u32_e32 v131, 0x84000, v130
	v_pk_mul_f32 v[14:15], v[14:15], v[244:245] op_sel_hi:[1,0]
	v_pk_mul_f32 v[16:17], v[16:17], v[244:245] op_sel_hi:[1,0]
	v_pk_mul_f32 v[6:7], v[6:7], v[244:245] op_sel_hi:[1,0]
	v_pk_mul_f32 v[8:9], v[8:9], v[244:245] op_sel_hi:[1,0]
	v_cvt_pk_bf16_f32 v208, v14, v15
	v_cvt_pk_bf16_f32 v209, v16, v17
	v_cvt_pk_bf16_f32 v210, v6, v7
	v_cvt_pk_bf16_f32 v211, v8, v9
	global_store_dwordx4 v131, v[208:211], s[12:13]
	v_pk_mul_f32 v[10:11], v[10:11], v[244:245] op_sel_hi:[1,0]
	v_pk_mul_f32 v[12:13], v[12:13], v[244:245] op_sel_hi:[1,0]
	v_pk_mul_f32 v[2:3], v[2:3], v[244:245] op_sel_hi:[1,0]
	v_pk_mul_f32 v[4:5], v[4:5], v[244:245] op_sel_hi:[1,0]
	v_cvt_pk_bf16_f32 v212, v10, v11
	v_cvt_pk_bf16_f32 v213, v12, v13
	v_cvt_pk_bf16_f32 v214, v2, v3
	v_cvt_pk_bf16_f32 v215, v4, v5
	global_store_dwordx4 v131, v[212:215], s[12:13] offset:384
	s_branch .LBB0_578
.Lqb_orig:
	s_cmp_gt_i32 s77, 3
	s_cselect_b64 s[12:13], -1, 0
	s_cmp_lt_i32 s77, 4
	s_cselect_b64 s[18:19], -1, 0
	s_mov_b64 s[2:3], s[96:97]
	s_mov_b64 s[14:15], -1
	s_and_b64 vcc, exec, s[18:19]
	s_cbranch_vccz .LBB0_527
	s_mul_i32 s14, s77, 0x180
	s_ashr_i32 s15, s14, 31
	s_lshl_b64 s[14:15], s[14:15], 1
	s_add_u32 s14, s2, s14
	v_readlane_b32 s16, v255, 1
	s_addc_u32 s15, s3, s15
	s_lshl_b32 s16, s16, 1
	s_add_u32 s14, s14, s16
	s_addc_u32 s15, s15, 0
	s_add_u32 s16, s14, 0x1e1c1000
	s_addc_u32 s17, s15, 0
	s_mov_b64 s[14:15], 0

; #define LAS __attribute__((address_space(3)))
; __device__ __forceinline__ unsigned pk2(float lo, float hi) { f32x2 v = {lo, hi}; bf16x2_t b = __builtin_convertvector(v, bf16x2_t); return __builtin_bit_cast(unsigned, b); }
; __device__ __forceinline__ void epi_swiglu(bf16_t* H, const LAS float* tbl, const f32x4 (&acc)[2][2][4][2], const Unit& u, int wr, int wc, int fr, int fq) {
;     const int col0 = u.pn * 128 + wc * 32 + fq * 8;
; #pragma unroll
;     for (int it = 0; it < 8; ++it) {
;         const int ai = it >> 2, m = it & 3; const int r = opaque(EPI_ROW(it));
;         const float rs = tbl[EPI_LROW(it)];
;         u32x4 w;
; #pragma unroll
;         for (int n = 0; n < 2; ++n) {
;             const f32x4 g = acc[ai][0][m][n] * rs, up = acc[ai][1][m][n] * rs; float hv[4];
; #pragma unroll
;             for (int i = 0; i < 4; ++i) hv[i] = g[i] * __builtin_amdgcn_rcpf(1.0f + __expf(-g[i])) * up[i];
;             w[2 * n] = pk2(hv[0], hv[1]); w[2 * n + 1] = pk2(hv[2], hv[3]);
;         }
;         *(u32x4*)(H + ((size_t)(r >> 8) * (DFF / 64) + (col0 >> 6)) * 16384 + (r & 255) * 64 + (col0 & 63)) = w;
;     }
; }
.LBB0_752:
	s_and_b64 vcc, exec, s[2:3]
	s_cbranch_vccz .LBB0_754
	s_mov_b64 s[2:3], s[96:97]
	s_add_u32 s2, s2, 0x17e00000
	s_addc_u32 s3, s3, 0
	s_lshl_b32 s12, s77, 7
	v_readlane_b32 s13, v255, 1
	s_or_b32 s12, s12, s13
	v_readlane_b32 s13, v254, 31
	s_lshl_b32 s13, s13, 2
	s_add_i32 s39, s39, s13
	s_lshl_b32 s14, s81, 8
	s_waitcnt lgkmcnt(0)
	v_add_u32_e32 v131, s14, v193
	v_lshl_add_u32 v130, v183, 2, s39
	ds_read_b32 v140, v130
	ds_read_b32 v141, v130 offset:64
	ds_read_b32 v142, v130 offset:128
	ds_read_b32 v143, v130 offset:192
	ds_read_b32 v144, v130 offset:512
	ds_read_b32 v145, v130 offset:576
	ds_read_b32 v146, v130 offset:640
	ds_read_b32 v147, v130 offset:704
	s_ashr_i32 s12, s12, 6
	s_ashr_i32 s13, s12, 31
	v_mov_b32_e32 v199, v0
	v_lshrrev_b32_e32 v132, 8, v131
	v_mul_i32_i24_e32 v132, 0x58, v132
	v_ashrrev_i32_e32 v133, 31, v132
	v_lshl_add_u64 v[132:133], v[132:133], 0, s[12:13]
	v_lshlrev_b64 v[132:133], 15, v[132:133]
	v_lshl_add_u64 v[132:133], s[2:3], 0, v[132:133]
	v_lshlrev_b32_e32 v134, 7, v131
	v_and_b32_e32 v134, 0x7f80, v134
	v_mov_b32_e32 v135, v0
	v_lshl_add_u64 v[132:133], v[132:133], 0, v[134:135]
	v_lshl_add_u64 v[132:133], v[132:133], 0, v[198:199]
	s_mov_b64 s[12:13], 0x1000
	s_mov_b64 s[14:15], 0x5000
	v_lshl_add_u64 v[134:135], v[132:133], 0, s[12:13]
	v_lshl_add_u64 v[136:137], v[132:133], 0, s[14:15]
	v_mov_b32_e32 v138, 1.0
	v_mov_b32_e32 v139, 1.0
	s_waitcnt lgkmcnt(0)
	v_mul_f32_e32 v148, 0xbfb8aa3b, v140
	v_mul_f32_e32 v150, v140, v140
	v_rcp_f32_e32 v150, v150
	v_pk_mul_f32 v[152:153], v[126:127], v[148:149] op_sel_hi:[1,0]
	v_pk_mul_f32 v[154:155], v[128:129], v[148:149] op_sel_hi:[1,0]
	v_pk_mul_f32 v[156:157], v[118:119], v[148:149] op_sel_hi:[1,0]
	v_pk_mul_f32 v[158:159], v[120:121], v[148:149] op_sel_hi:[1,0]
	v_exp_f32_e32 v152, v152
	v_exp_f32_e32 v153, v153
	v_exp_f32_e32 v154, v154
	v_exp_f32_e32 v155, v155
	v_exp_f32_e32 v156, v156
	v_exp_f32_e32 v157, v157
	v_exp_f32_e32 v158, v158
	v_exp_f32_e32 v159, v159
	v_pk_mul_f32 v[126:127], v[126:127], v[122:123]
	v_pk_mul_f32 v[128:129], v[128:129], v[124:125]
	v_pk_mul_f32 v[118:119], v[118:119], v[114:115]
	v_pk_mul_f32 v[120:121], v[120:121], v[116:117]
	v_pk_fma_f32 v[152:153], v[152:153], v[150:151], v[150:151] op_sel_hi:[1,0,0]
	v_pk_fma_f32 v[154:155], v[154:155], v[150:151], v[150:151] op_sel_hi:[1,0,0]
	v_pk_fma_f32 v[156:157], v[156:157], v[150:151], v[150:151] op_sel_hi:[1,0,0]
	v_pk_fma_f32 v[158:159], v[158:159], v[150:151], v[150:151] op_sel_hi:[1,0,0]
	v_rcp_f32_e32 v152, v152
	v_rcp_f32_e32 v153, v153
	v_rcp_f32_e32 v154, v154
	v_rcp_f32_e32 v155, v155
	v_rcp_f32_e32 v156, v156
	v_rcp_f32_e32 v157, v157
	v_rcp_f32_e32 v158, v158
	v_rcp_f32_e32 v159, v159
	v_pk_mul_f32 v[126:127], v[126:127], v[152:153]
	v_pk_mul_f32 v[128:129], v[128:129], v[154:155]
	v_pk_mul_f32 v[118:119], v[118:119], v[156:157]
	v_pk_mul_f32 v[120:121], v[120:121], v[158:159]
	v_cvt_pk_bf16_f32 v160, v126, v127
	v_cvt_pk_bf16_f32 v161, v128, v129
	v_cvt_pk_bf16_f32 v162, v118, v119
	v_cvt_pk_bf16_f32 v163, v120, v121
	global_store_dwordx4 v[134:135], v[160:163], off offset:-4096
	v_mul_f32_e32 v148, 0xbfb8aa3b, v141
	v_mul_f32_e32 v150, v141, v141
	v_rcp_f32_e32 v150, v150
	v_pk_mul_f32 v[152:153], v[110:111], v[148:149] op_sel_hi:[1,0]
	v_pk_mul_f32 v[154:155], v[112:113], v[148:149] op_sel_hi:[1,0]
	v_pk_mul_f32 v[156:157], v[102:103], v[148:149] op_sel_hi:[1,0]
	v_pk_mul_f32 v[158:159], v[104:105], v[148:149] op_sel_hi:[1,0]
	v_exp_f32_e32 v152, v152
	v_exp_f32_e32 v153, v153
	v_exp_f32_e32 v154, v154
	v_exp_f32_e32 v155, v155
	v_exp_f32_e32 v156, v156
	v_exp_f32_e32 v157, v157
	v_exp_f32_e32 v158, v158
	v_exp_f32_e32 v159, v159
	v_pk_mul_f32 v[110:111], v[110:111], v[106:107]
	v_pk_mul_f32 v[112:113], v[112:113], v[108:109]
	v_pk_mul_f32 v[102:103], v[102:103], v[98:99]
	v_pk_mul_f32 v[104:105], v[104:105], v[100:101]
	v_pk_fma_f32 v[152:153], v[152:153], v[150:151], v[150:151] op_sel_hi:[1,0,0]
	v_pk_fma_f32 v[154:155], v[154:155], v[150:151], v[150:151] op_sel_hi:[1,0,0]
	v_pk_fma_f32 v[156:157], v[156:157], v[150:151], v[150:151] op_sel_hi:[1,0,0]
	v_pk_fma_f32 v[158:159], v[158:159], v[150:151], v[150:151] op_sel_hi:[1,0,0]
	v_rcp_f32_e32 v152, v152
	v_rcp_f32_e32 v153, v153
	v_rcp_f32_e32 v154, v154
	v_rcp_f32_e32 v155, v155
	v_rcp_f32_e32 v156, v156
	v_rcp_f32_e32 v157, v157
	v_rcp_f32_e32 v158, v158
	v_rcp_f32_e32 v159, v159
	v_pk_mul_f32 v[110:111], v[110:111], v[152:153]
	v_pk_mul_f32 v[112:113], v[112:113], v[154:155]
	v_pk_mul_f32 v[102:103], v[102:103], v[156:157]
	v_pk_mul_f32 v[104:105], v[104:105], v[158:159]
	v_cvt_pk_bf16_f32 v164, v110, v111
	v_cvt_pk_bf16_f32 v165, v112, v113
	v_cvt_pk_bf16_f32 v166, v102, v103
	v_cvt_pk_bf16_f32 v167, v104, v105
	global_store_dwordx4 v[134:135], v[164:167], off offset:-2048
	v_mul_f32_e32 v148, 0xbfb8aa3b, v142
	v_mul_f32_e32 v150, v142, v142
	v_rcp_f32_e32 v150, v150
	v_pk_mul_f32 v[152:153], v[94:95], v[148:149] op_sel_hi:[1,0]
	v_pk_mul_f32 v[154:155], v[96:97], v[148:149] op_sel_hi:[1,0]
	v_pk_mul_f32 v[156:157], v[86:87], v[148:149] op_sel_hi:[1,0]
	v_pk_mul_f32 v[158:159], v[88:89], v[148:149] op_sel_hi:[1,0]
	v_exp_f32_e32 v152, v152
	v_exp_f32_e32 v153, v153
	v_exp_f32_e32 v154, v154
	v_exp_f32_e32 v155, v155
	v_exp_f32_e32 v156, v156
	v_exp_f32_e32 v157, v157
	v_exp_f32_e32 v158, v158
	v_exp_f32_e32 v159, v159
	v_pk_mul_f32 v[94:95], v[94:95], v[90:91]
	v_pk_mul_f32 v[96:97], v[96:97], v[92:93]
	v_pk_mul_f32 v[86:87], v[86:87], v[82:83]
	v_pk_mul_f32 v[88:89], v[88:89], v[84:85]
	v_pk_fma_f32 v[152:153], v[152:153], v[150:151], v[150:151] op_sel_hi:[1,0,0]
; __device__ __forceinline__ unsigned pk2(float lo, float hi) { f32x2 v = {lo, hi}; bf16x2_t b = __builtin_convertvector(v, bf16x2_t); return __builtin_bit_cast(unsigned, b); }
; __device__ __forceinline__ void epi_swiglu(bf16_t* H, const LAS float* tbl, const f32x4 (&acc)[2][2][4][2], const Unit& u, int wr, int wc, int fr, int fq) {
;     ...
;     for (int it = 0; it < 8; ++it) {
;         const int ai = it >> 2, m = it & 3; const int r = opaque(EPI_ROW(it));
;         const float rs = tbl[EPI_LROW(it)];
;         u32x4 w;
; #pragma unroll
;         for (int n = 0; n < 2; ++n) {
;             const f32x4 g = acc[ai][0][m][n] * rs, up = acc[ai][1][m][n] * rs; float hv[4];
; #pragma unroll
;             for (int i = 0; i < 4; ++i) hv[i] = g[i] * __builtin_amdgcn_rcpf(1.0f + __expf(-g[i])) * up[i];
;             w[2 * n] = pk2(hv[0], hv[1]); w[2 * n + 1] = pk2(hv[2], hv[3]);
;         }
;         *(u32x4*)(H + ((size_t)(r >> 8) * (DFF / 64) + (col0 >> 6)) * 16384 + (r & 255) * 64 + (col0 & 63)) = w;
;     }
	v_pk_fma_f32 v[154:155], v[154:155], v[150:151], v[150:151] op_sel_hi:[1,0,0]
	v_pk_fma_f32 v[156:157], v[156:157], v[150:151], v[150:151] op_sel_hi:[1,0,0]
	v_pk_fma_f32 v[158:159], v[158:159], v[150:151], v[150:151] op_sel_hi:[1,0,0]
	v_rcp_f32_e32 v152, v152
	v_rcp_f32_e32 v153, v153
	v_rcp_f32_e32 v154, v154
	v_rcp_f32_e32 v155, v155
	v_rcp_f32_e32 v156, v156
	v_rcp_f32_e32 v157, v157
	v_rcp_f32_e32 v158, v158
	v_rcp_f32_e32 v159, v159
	v_pk_mul_f32 v[94:95], v[94:95], v[152:153]
	v_pk_mul_f32 v[96:97], v[96:97], v[154:155]
	v_pk_mul_f32 v[86:87], v[86:87], v[156:157]
	v_pk_mul_f32 v[88:89], v[88:89], v[158:159]
	v_cvt_pk_bf16_f32 v160, v94, v95
	v_cvt_pk_bf16_f32 v161, v96, v97
	v_cvt_pk_bf16_f32 v162, v86, v87
	v_cvt_pk_bf16_f32 v163, v88, v89
	global_store_dwordx4 v[134:135], v[160:163], off
	v_mul_f32_e32 v148, 0xbfb8aa3b, v143
	v_mul_f32_e32 v150, v143, v143
	v_rcp_f32_e32 v150, v150
	v_pk_mul_f32 v[152:153], v[78:79], v[148:149] op_sel_hi:[1,0]
	v_pk_mul_f32 v[154:155], v[80:81], v[148:149] op_sel_hi:[1,0]
	v_pk_mul_f32 v[156:157], v[70:71], v[148:149] op_sel_hi:[1,0]
	v_pk_mul_f32 v[158:159], v[72:73], v[148:149] op_sel_hi:[1,0]
	v_exp_f32_e32 v152, v152
	v_exp_f32_e32 v153, v153
	v_exp_f32_e32 v154, v154
	v_exp_f32_e32 v155, v155
	v_exp_f32_e32 v156, v156
	v_exp_f32_e32 v157, v157
	v_exp_f32_e32 v158, v158
	v_exp_f32_e32 v159, v159
	v_pk_mul_f32 v[78:79], v[78:79], v[74:75]
	v_pk_mul_f32 v[80:81], v[80:81], v[76:77]
	v_pk_mul_f32 v[70:71], v[70:71], v[66:67]
	v_pk_mul_f32 v[72:73], v[72:73], v[68:69]
	v_pk_fma_f32 v[152:153], v[152:153], v[150:151], v[150:151] op_sel_hi:[1,0,0]
	v_pk_fma_f32 v[154:155], v[154:155], v[150:151], v[150:151] op_sel_hi:[1,0,0]
	v_pk_fma_f32 v[156:157], v[156:157], v[150:151], v[150:151] op_sel_hi:[1,0,0]
	v_pk_fma_f32 v[158:159], v[158:159], v[150:151], v[150:151] op_sel_hi:[1,0,0]
	v_rcp_f32_e32 v152, v152
	v_rcp_f32_e32 v153, v153
	v_rcp_f32_e32 v154, v154
	v_rcp_f32_e32 v155, v155
	v_rcp_f32_e32 v156, v156
	v_rcp_f32_e32 v157, v157
	v_rcp_f32_e32 v158, v158
	v_rcp_f32_e32 v159, v159
	v_pk_mul_f32 v[78:79], v[78:79], v[152:153]
	v_pk_mul_f32 v[80:81], v[80:81], v[154:155]
	v_pk_mul_f32 v[70:71], v[70:71], v[156:157]
	v_pk_mul_f32 v[72:73], v[72:73], v[158:159]
	v_cvt_pk_bf16_f32 v164, v78, v79
	v_cvt_pk_bf16_f32 v165, v80, v81
	v_cvt_pk_bf16_f32 v166, v70, v71
	v_cvt_pk_bf16_f32 v167, v72, v73
	global_store_dwordx4 v[134:135], v[164:167], off offset:2048
	v_mul_f32_e32 v148, 0xbfb8aa3b, v144
	v_mul_f32_e32 v150, v144, v144
	v_rcp_f32_e32 v150, v150
	v_pk_mul_f32 v[152:153], v[62:63], v[148:149] op_sel_hi:[1,0]
	v_pk_mul_f32 v[154:155], v[64:65], v[148:149] op_sel_hi:[1,0]
	v_pk_mul_f32 v[156:157], v[54:55], v[148:149] op_sel_hi:[1,0]
	v_pk_mul_f32 v[158:159], v[56:57], v[148:149] op_sel_hi:[1,0]
	v_exp_f32_e32 v152, v152
	v_exp_f32_e32 v153, v153
	v_exp_f32_e32 v154, v154
	v_exp_f32_e32 v155, v155
	v_exp_f32_e32 v156, v156
	v_exp_f32_e32 v157, v157
	v_exp_f32_e32 v158, v158
	v_exp_f32_e32 v159, v159
	v_pk_mul_f32 v[62:63], v[62:63], v[58:59]
	v_pk_mul_f32 v[64:65], v[64:65], v[60:61]
	v_pk_mul_f32 v[54:55], v[54:55], v[50:51]
	v_pk_mul_f32 v[56:57], v[56:57], v[52:53]
	v_pk_fma_f32 v[152:153], v[152:153], v[150:151], v[150:151] op_sel_hi:[1,0,0]
	v_pk_fma_f32 v[154:155], v[154:155], v[150:151], v[150:151] op_sel_hi:[1,0,0]
	v_pk_fma_f32 v[156:157], v[156:157], v[150:151], v[150:151] op_sel_hi:[1,0,0]
	v_pk_fma_f32 v[158:159], v[158:159], v[150:151], v[150:151] op_sel_hi:[1,0,0]
	v_rcp_f32_e32 v152, v152
	v_rcp_f32_e32 v153, v153
	v_rcp_f32_e32 v154, v154
	v_rcp_f32_e32 v155, v155
	v_rcp_f32_e32 v156, v156
	v_rcp_f32_e32 v157, v157
	v_rcp_f32_e32 v158, v158
	v_rcp_f32_e32 v159, v159
	v_pk_mul_f32 v[62:63], v[62:63], v[152:153]
	v_pk_mul_f32 v[64:65], v[64:65], v[154:155]
	v_pk_mul_f32 v[54:55], v[54:55], v[156:157]
	v_pk_mul_f32 v[56:57], v[56:57], v[158:159]
	v_cvt_pk_bf16_f32 v160, v62, v63
	v_cvt_pk_bf16_f32 v161, v64, v65
	v_cvt_pk_bf16_f32 v162, v54, v55
	v_cvt_pk_bf16_f32 v163, v56, v57
	global_store_dwordx4 v[136:137], v[160:163], off offset:-4096
	v_mul_f32_e32 v148, 0xbfb8aa3b, v145
	v_mul_f32_e32 v150, v145, v145
	v_rcp_f32_e32 v150, v150
	v_pk_mul_f32 v[152:153], v[46:47], v[148:149] op_sel_hi:[1,0]
	v_pk_mul_f32 v[154:155], v[48:49], v[148:149] op_sel_hi:[1,0]
	v_pk_mul_f32 v[156:157], v[38:39], v[148:149] op_sel_hi:[1,0]
	v_pk_mul_f32 v[158:159], v[40:41], v[148:149] op_sel_hi:[1,0]
	v_exp_f32_e32 v152, v152
	v_exp_f32_e32 v153, v153
; __device__ __forceinline__ unsigned pk2(float lo, float hi) { f32x2 v = {lo, hi}; bf16x2_t b = __builtin_convertvector(v, bf16x2_t); return __builtin_bit_cast(unsigned, b); }
; __device__ __forceinline__ void epi_swiglu(bf16_t* H, const LAS float* tbl, const f32x4 (&acc)[2][2][4][2], const Unit& u, int wr, int wc, int fr, int fq) {
;     ...
;     for (int it = 0; it < 8; ++it) {
;         const int ai = it >> 2, m = it & 3; const int r = opaque(EPI_ROW(it));
;         const float rs = tbl[EPI_LROW(it)];
;         u32x4 w;
; #pragma unroll
;         for (int n = 0; n < 2; ++n) {
;             const f32x4 g = acc[ai][0][m][n] * rs, up = acc[ai][1][m][n] * rs; float hv[4];
; #pragma unroll
;             for (int i = 0; i < 4; ++i) hv[i] = g[i] * __builtin_amdgcn_rcpf(1.0f + __expf(-g[i])) * up[i];
;             w[2 * n] = pk2(hv[0], hv[1]); w[2 * n + 1] = pk2(hv[2], hv[3]);
;         }
;         *(u32x4*)(H + ((size_t)(r >> 8) * (DFF / 64) + (col0 >> 6)) * 16384 + (r & 255) * 64 + (col0 & 63)) = w;
;     }
	v_exp_f32_e32 v154, v154
	v_exp_f32_e32 v155, v155
	v_exp_f32_e32 v156, v156
	v_exp_f32_e32 v157, v157
	v_exp_f32_e32 v158, v158
	v_exp_f32_e32 v159, v159
	v_pk_mul_f32 v[46:47], v[46:47], v[42:43]
	v_pk_mul_f32 v[48:49], v[48:49], v[44:45]
	v_pk_mul_f32 v[38:39], v[38:39], v[34:35]
	v_pk_mul_f32 v[40:41], v[40:41], v[36:37]
	v_pk_fma_f32 v[152:153], v[152:153], v[150:151], v[150:151] op_sel_hi:[1,0,0]
	v_pk_fma_f32 v[154:155], v[154:155], v[150:151], v[150:151] op_sel_hi:[1,0,0]
	v_pk_fma_f32 v[156:157], v[156:157], v[150:151], v[150:151] op_sel_hi:[1,0,0]
	v_pk_fma_f32 v[158:159], v[158:159], v[150:151], v[150:151] op_sel_hi:[1,0,0]
	v_rcp_f32_e32 v152, v152
	v_rcp_f32_e32 v153, v153
	v_rcp_f32_e32 v154, v154
	v_rcp_f32_e32 v155, v155
	v_rcp_f32_e32 v156, v156
	v_rcp_f32_e32 v157, v157
	v_rcp_f32_e32 v158, v158
	v_rcp_f32_e32 v159, v159
	v_pk_mul_f32 v[46:47], v[46:47], v[152:153]
	v_pk_mul_f32 v[48:49], v[48:49], v[154:155]
	v_pk_mul_f32 v[38:39], v[38:39], v[156:157]
	v_pk_mul_f32 v[40:41], v[40:41], v[158:159]
	v_cvt_pk_bf16_f32 v164, v46, v47
	v_cvt_pk_bf16_f32 v165, v48, v49
	v_cvt_pk_bf16_f32 v166, v38, v39
	v_cvt_pk_bf16_f32 v167, v40, v41
	global_store_dwordx4 v[136:137], v[164:167], off offset:-2048
	v_mul_f32_e32 v148, 0xbfb8aa3b, v146
	v_mul_f32_e32 v150, v146, v146
	v_rcp_f32_e32 v150, v150
	v_pk_mul_f32 v[152:153], v[30:31], v[148:149] op_sel_hi:[1,0]
	v_pk_mul_f32 v[154:155], v[32:33], v[148:149] op_sel_hi:[1,0]
	v_pk_mul_f32 v[156:157], v[22:23], v[148:149] op_sel_hi:[1,0]
	v_pk_mul_f32 v[158:159], v[24:25], v[148:149] op_sel_hi:[1,0]
	v_exp_f32_e32 v152, v152
	v_exp_f32_e32 v153, v153
	v_exp_f32_e32 v154, v154
	v_exp_f32_e32 v155, v155
	v_exp_f32_e32 v156, v156
	v_exp_f32_e32 v157, v157
	v_exp_f32_e32 v158, v158
	v_exp_f32_e32 v159, v159
	v_pk_mul_f32 v[30:31], v[30:31], v[26:27]
	v_pk_mul_f32 v[32:33], v[32:33], v[28:29]
	v_pk_mul_f32 v[22:23], v[22:23], v[18:19]
	v_pk_mul_f32 v[24:25], v[24:25], v[20:21]
	v_pk_fma_f32 v[152:153], v[152:153], v[150:151], v[150:151] op_sel_hi:[1,0,0]
	v_pk_fma_f32 v[154:155], v[154:155], v[150:151], v[150:151] op_sel_hi:[1,0,0]
	v_pk_fma_f32 v[156:157], v[156:157], v[150:151], v[150:151] op_sel_hi:[1,0,0]
	v_pk_fma_f32 v[158:159], v[158:159], v[150:151], v[150:151] op_sel_hi:[1,0,0]
	v_rcp_f32_e32 v152, v152
	v_rcp_f32_e32 v153, v153
	v_rcp_f32_e32 v154, v154
	v_rcp_f32_e32 v155, v155
	v_rcp_f32_e32 v156, v156
	v_rcp_f32_e32 v157, v157
	v_rcp_f32_e32 v158, v158
	v_rcp_f32_e32 v159, v159
	v_pk_mul_f32 v[30:31], v[30:31], v[152:153]
	v_pk_mul_f32 v[32:33], v[32:33], v[154:155]
	v_pk_mul_f32 v[22:23], v[22:23], v[156:157]
	v_pk_mul_f32 v[24:25], v[24:25], v[158:159]
	v_cvt_pk_bf16_f32 v160, v30, v31
	v_cvt_pk_bf16_f32 v161, v32, v33
	v_cvt_pk_bf16_f32 v162, v22, v23
	v_cvt_pk_bf16_f32 v163, v24, v25
	global_store_dwordx4 v[136:137], v[160:163], off
	v_mul_f32_e32 v148, 0xbfb8aa3b, v147
	v_mul_f32_e32 v150, v147, v147
	v_rcp_f32_e32 v150, v150
	v_pk_mul_f32 v[152:153], v[14:15], v[148:149] op_sel_hi:[1,0]
	v_pk_mul_f32 v[154:155], v[16:17], v[148:149] op_sel_hi:[1,0]
	v_pk_mul_f32 v[156:157], v[6:7], v[148:149] op_sel_hi:[1,0]
	v_pk_mul_f32 v[158:159], v[8:9], v[148:149] op_sel_hi:[1,0]
	v_exp_f32_e32 v152, v152
	v_exp_f32_e32 v153, v153
	v_exp_f32_e32 v154, v154
	v_exp_f32_e32 v155, v155
	v_exp_f32_e32 v156, v156
	v_exp_f32_e32 v157, v157
	v_exp_f32_e32 v158, v158
	v_exp_f32_e32 v159, v159
	v_pk_mul_f32 v[14:15], v[14:15], v[10:11]
	v_pk_mul_f32 v[16:17], v[16:17], v[12:13]
	v_pk_mul_f32 v[6:7], v[6:7], v[2:3]
	v_pk_mul_f32 v[8:9], v[8:9], v[4:5]
	v_pk_fma_f32 v[152:153], v[152:153], v[150:151], v[150:151] op_sel_hi:[1,0,0]
	v_pk_fma_f32 v[154:155], v[154:155], v[150:151], v[150:151] op_sel_hi:[1,0,0]
	v_pk_fma_f32 v[156:157], v[156:157], v[150:151], v[150:151] op_sel_hi:[1,0,0]
	v_pk_fma_f32 v[158:159], v[158:159], v[150:151], v[150:151] op_sel_hi:[1,0,0]
	v_rcp_f32_e32 v152, v152
	v_rcp_f32_e32 v153, v153
	v_rcp_f32_e32 v154, v154
	v_rcp_f32_e32 v155, v155
	v_rcp_f32_e32 v156, v156
	v_rcp_f32_e32 v157, v157
	v_rcp_f32_e32 v158, v158
	v_rcp_f32_e32 v159, v159
	v_pk_mul_f32 v[14:15], v[14:15], v[152:153]
	v_pk_mul_f32 v[16:17], v[16:17], v[154:155]
	v_pk_mul_f32 v[6:7], v[6:7], v[156:157]
	v_pk_mul_f32 v[8:9], v[8:9], v[158:159]
	v_cvt_pk_bf16_f32 v164, v14, v15
	v_cvt_pk_bf16_f32 v165, v16, v17
	v_cvt_pk_bf16_f32 v166, v6, v7
	v_cvt_pk_bf16_f32 v167, v8, v9
	global_store_dwordx4 v[136:137], v[164:167], off offset:2048
